# ph0: context-cache conversion coalesced (V tile transposed in LDS); norm+modulate rows rebalanced: bid<128 (two adaLN items) take 4 rows per wave, the others 8
# speedup vs baseline: 1.0476x; 1.0099x over previous
.LBB0_1125:
	s_cmpk_lg_u32 s24, 0x100
	s_cbranch_scc1 .Lkv_orig
	s_barrier
	s_lshl_b32 s40, s56, 14
	v_lshlrev_b32_e32 v1, 4, v192
	v_add_u32_e32 v1, s40, v1
	v_add_u32_e32 v2, 0x2000, v1
	global_load_dwordx4 v[4:7], v1, s[8:9]
	global_load_dwordx4 v[8:11], v2, s[8:9]
	global_load_dwordx4 v[12:15], v1, s[10:11]
	global_load_dwordx4 v[16:19], v2, s[10:11]
	v_readlane_b32 s36, v253, 12
	v_readlane_b32 s37, v253, 13
	s_lshl_b32 s40, s56, 13
	v_lshl_add_u32 v3, v192, 3, s40
	v_add_u32_e32 v24, 0x1000, v3
	s_add_u32 s38, s36, 0x200000
	s_addc_u32 s39, s37, 0
	v_and_b32_e32 v25, 15, v192
	v_mul_u32_u24_e32 v25, 0x240, v25
	v_lshrrev_b32_e32 v26, 4, v192
	v_lshl_add_u32 v25, v26, 1, v25
	v_lshrrev_b32_e32 v29, 3, v192
	v_and_b32_e32 v30, 7, v192
	v_lshlrev_b32_e32 v31, 9, v29
	v_mul_u32_u24_e32 v29, 0x90, v29
	v_lshl_add_u32 v29, v30, 4, v29
	v_lshl_add_u32 v31, v30, 4, v31
	s_lshr_b32 s40, s56, 2
	s_lshl_b32 s40, s40, 15
	s_and_b32 s41, s56, 3
	s_lshl_b32 s41, s41, 7
	s_add_i32 s40, s40, s41
	v_add_u32_e32 v31, s40, v31
	s_waitcnt vmcnt(3)
	v_cvt_pk_bf16_f32 v20, v4, v5
	v_cvt_pk_bf16_f32 v21, v6, v7
	global_store_dwordx2 v3, v[20:21], s[36:37]
	s_waitcnt vmcnt(3)
	v_cvt_pk_bf16_f32 v22, v8, v9
	v_cvt_pk_bf16_f32 v23, v10, v11
	global_store_dwordx2 v24, v[22:23], s[36:37]
	s_waitcnt vmcnt(3)
	v_cvt_pk_bf16_f32 v27, v12, v13
	v_cvt_pk_bf16_f32 v28, v14, v15
	ds_write_b16 v25, v27
	ds_write_b16_d16_hi v25, v27 offset:144
	ds_write_b16 v25, v28 offset:288
	ds_write_b16_d16_hi v25, v28 offset:432
	s_waitcnt vmcnt(2)
	v_cvt_pk_bf16_f32 v27, v16, v17
	v_cvt_pk_bf16_f32 v28, v18, v19
	ds_write_b16 v25, v27 offset:64
	ds_write_b16_d16_hi v25, v27 offset:208
	ds_write_b16 v25, v28 offset:352
	ds_write_b16_d16_hi v25, v28 offset:496
	s_waitcnt lgkmcnt(0)
	s_barrier
	ds_read_b128 v[32:35], v29
	s_waitcnt lgkmcnt(0)
	global_store_dwordx4 v31, v[32:35], s[38:39]
	s_barrier
	s_mov_b64 s[22:23], exec
	s_branch .LBB0_1128

.LBB0_1141:
	global_load_dwordx4 v[32:35], v30, s[40:41]
	global_load_dwordx4 v[36:39], v30, s[40:41] offset:1024
	global_load_dwordx4 v[16:19], v30, s[40:41] offset:3072
	global_load_dwordx4 v[40:43], v30, s[40:41] offset:2048
	s_lshr_b32 s24, s26, 10
	s_add_i32 s24, s24, 1
	s_and_b64 s[34:35], s[38:39], exec
	s_cselect_b32 s24, 0, s24
	v_mad_u64_u32 v[52:53], s[34:35], s24, v223, v[20:21]
	v_add_co_u32_e32 v54, vcc, s33, v52
	s_lshl_b64 s[0:1], s[0:1], 11
	s_nop 0
	v_addc_co_u32_e32 v55, vcc, 0, v53, vcc
	global_load_dwordx4 v[44:47], v[54:55], off
	global_load_dwordx4 v[48:51], v[52:53], off
	s_cmpk_lg_u32 s20, 0x800
	s_cbranch_scc1 .Ln1_orig
	s_cmpk_lt_i32 s2, 0x1800
	s_cbranch_scc1 .Ln1_orig
	s_cmp_lt_u32 s56, 128
	s_cbranch_scc1 .Ln1_stop
	s_add_u32 s2, s2, 0x400
	s_addc_u32 s3, s3, 0
	s_branch .Ln1_next
.Ln1_stop:
	s_movk_i32 s2, 0x3000
	s_mov_b32 s3, 0
	s_branch .Ln1_next
.Ln1_orig:
	s_add_u32 s2, s2, s20
	s_addc_u32 s3, s3, s21
.Ln1_next:
	s_add_u32 s22, s22, s36
	s_addc_u32 s23, s23, s37
	s_cmpk_gt_i32 s2, 0x2fff
	s_waitcnt vmcnt(5)
	v_pk_mul_f32 v[56:57], v[34:35], v[34:35]
	v_pk_mul_f32 v[58:59], v[32:33], v[32:33]
	s_waitcnt vmcnt(4)
	v_pk_mul_f32 v[60:61], v[38:39], v[38:39]
	v_pk_mul_f32 v[62:63], v[36:37], v[36:37]
	v_pk_mov_b32 v[68:69], v[58:59], v[56:57] op_sel:[1,0]
	v_mov_b32_e32 v59, v57
	v_pk_mov_b32 v[56:57], v[62:63], v[60:61] op_sel:[1,0]
	v_mov_b32_e32 v63, v61
	s_waitcnt vmcnt(3)
	v_mul_f32_e32 v67, v17, v17
	s_waitcnt vmcnt(2)
	v_mul_f32_e32 v64, v41, v41
	v_mul_f32_e32 v66, v43, v43
	v_pk_add_f32 v[58:59], v[68:69], v[58:59]
	v_pk_add_f32 v[56:57], v[56:57], v[62:63]
	v_mul_f32_e32 v31, v16, v16
	v_mul_f32_e32 v70, v18, v18
	v_mul_f32_e32 v71, v19, v19
	v_pk_fma_f32 v[60:61], v[40:41], v[40:41], v[64:65] op_sel_hi:[1,1,0]
	v_pk_fma_f32 v[64:65], v[42:43], v[42:43], v[66:67] op_sel_hi:[1,1,0]
	v_pk_add_f32 v[58:59], v[58:59], v[58:59] op_sel:[0,1] op_sel_hi:[1,0]
	v_pk_add_f32 v[56:57], v[56:57], v[56:57] op_sel:[0,1] op_sel_hi:[1,0]
	v_mov_b32_e32 v61, v70
	v_mov_b32_e32 v65, v71
	v_mov_b32_e32 v59, v31
	v_mov_b32_e32 v57, v67
	v_pk_add_f32 v[60:61], v[60:61], v[64:65]
	v_pk_add_f32 v[56:57], v[58:59], v[56:57]
	s_waitcnt vmcnt(1)
	v_pk_add_f32 v[44:45], v[44:45], 1.0 op_sel_hi:[1,0]
	v_pk_add_f32 v[56:57], v[56:57], v[60:61]
	v_pk_add_f32 v[46:47], v[46:47], 1.0 op_sel_hi:[1,0]
	v_add_f32_e32 v31, v56, v57
	ds_bpermute_b32 v56, v24, v31
	s_waitcnt lgkmcnt(0)
	v_add_f32_e32 v31, v31, v56
	ds_bpermute_b32 v56, v25, v31
	s_waitcnt lgkmcnt(0)
	v_add_f32_e32 v31, v31, v56
	ds_bpermute_b32 v56, v26, v31
	s_waitcnt lgkmcnt(0)
	v_add_f32_e32 v31, v31, v56
	ds_bpermute_b32 v56, v27, v31
	s_waitcnt lgkmcnt(0)
	v_add_f32_e32 v31, v31, v56
	ds_bpermute_b32 v56, v28, v31
	s_waitcnt lgkmcnt(0)
	v_add_f32_e32 v31, v31, v56
	ds_bpermute_b32 v56, v29, v31
	s_waitcnt lgkmcnt(0)
	v_add_f32_e32 v31, v31, v56
	v_fmamk_f32 v31, v31, 0x3a800000, v217
	v_mul_f32_e32 v56, 0x4f800000, v31
	v_cmp_gt_f32_e32 vcc, s44, v31
	s_nop 1
	v_cndmask_b32_e32 v31, v31, v56, vcc
	v_sqrt_f32_e32 v58, v31
	v_lshl_add_u64 v[56:57], v[22:23], 0, s[0:1]
	v_add_u32_e32 v59, -1, v58
	v_add_u32_e32 v60, 1, v58
	v_fma_f32 v61, -v59, v58, v31
	v_fma_f32 v62, -v60, v58, v31
	v_cmp_ge_f32_e64 s[0:1], 0, v61
	s_nop 1
	v_cndmask_b32_e64 v58, v58, v59, s[0:1]
	v_cmp_lt_f32_e64 s[0:1], 0, v62
	s_nop 1
	v_cndmask_b32_e64 v58, v58, v60, s[0:1]
	v_mul_f32_e32 v59, 0x37800000, v58
	v_cndmask_b32_e32 v58, v58, v59, vcc
	v_cmp_class_f32_e32 vcc, v31, v218
	s_nop 1
	v_cndmask_b32_e32 v31, v58, v31, vcc
	v_div_scale_f32 v58, s[0:1], v31, v31, 1.0
	v_rcp_f32_e32 v59, v58
	v_div_scale_f32 v60, vcc, 1.0, v31, 1.0
	v_fma_f32 v61, -v58, v59, 1.0
	v_fmac_f32_e32 v59, v61, v59
	v_mul_f32_e32 v61, v60, v59
	v_fma_f32 v62, -v58, v61, v60
	v_fmac_f32_e32 v61, v62, v59
	v_fma_f32 v58, -v58, v61, v60
	v_div_fmas_f32 v58, v58, v59, v61
	v_div_fixup_f32 v58, v58, v31, 1.0
	v_pk_mul_f32 v[32:33], v[32:33], v[58:59] op_sel_hi:[1,0]
	v_pk_mul_f32 v[34:35], v[34:35], v[58:59] op_sel_hi:[1,0]
	v_pk_mul_f32 v[32:33], v[0:1], v[32:33]
	v_pk_mul_f32 v[34:35], v[2:3], v[34:35]
	s_waitcnt vmcnt(0)
	v_pk_fma_f32 v[32:33], v[44:45], v[32:33], v[48:49]
	v_pk_fma_f32 v[34:35], v[46:47], v[34:35], v[50:51]
	v_cvt_pk_bf16_f32 v32, v32, v33
	v_pk_mul_f32 v[36:37], v[36:37], v[58:59] op_sel_hi:[1,0]
	v_cvt_pk_bf16_f32 v33, v34, v35
	global_store_dwordx2 v[56:57], v[32:33], off
	global_load_dwordx4 v[32:35], v[54:55], off offset:1024
	s_nop 0
	global_load_dwordx4 v[44:47], v[52:53], off offset:1024
	v_pk_mul_f32 v[38:39], v[38:39], v[58:59] op_sel_hi:[1,0]
	v_pk_mul_f32 v[36:37], v[4:5], v[36:37]
	v_pk_mul_f32 v[38:39], v[6:7], v[38:39]
	v_pk_mul_f32 v[40:41], v[40:41], v[58:59] op_sel_hi:[1,0]
	v_pk_mul_f32 v[42:43], v[42:43], v[58:59] op_sel_hi:[1,0]
	v_pk_mul_f32 v[40:41], v[8:9], v[40:41]
	v_pk_mul_f32 v[42:43], v[10:11], v[42:43]
	v_pk_mul_f32 v[16:17], v[16:17], v[58:59] op_sel_hi:[1,0]
	v_pk_mul_f32 v[18:19], v[18:19], v[58:59] op_sel_hi:[1,0]
	v_pk_mul_f32 v[16:17], v[12:13], v[16:17]
	v_pk_mul_f32 v[18:19], v[14:15], v[18:19]
	s_waitcnt vmcnt(1)
	v_pk_add_f32 v[32:33], v[32:33], 1.0 op_sel_hi:[1,0]
	v_pk_add_f32 v[34:35], v[34:35], 1.0 op_sel_hi:[1,0]
	s_waitcnt vmcnt(0)
	v_pk_fma_f32 v[32:33], v[32:33], v[36:37], v[44:45]
	v_pk_fma_f32 v[34:35], v[34:35], v[38:39], v[46:47]
	v_cvt_pk_bf16_f32 v32, v32, v33
	s_nop 0
	v_cvt_pk_bf16_f32 v33, v34, v35
	global_store_dwordx2 v[56:57], v[32:33], off offset:512
	global_load_dwordx4 v[32:35], v[54:55], off offset:2048
	s_nop 0
	global_load_dwordx4 v[36:39], v[52:53], off offset:2048
	s_waitcnt vmcnt(1)
	v_pk_add_f32 v[32:33], v[32:33], 1.0 op_sel_hi:[1,0]
	v_pk_add_f32 v[34:35], v[34:35], 1.0 op_sel_hi:[1,0]
	s_waitcnt vmcnt(0)
	v_pk_fma_f32 v[32:33], v[40:41], v[32:33], v[36:37]
	v_pk_fma_f32 v[34:35], v[42:43], v[34:35], v[38:39]
	v_cvt_pk_bf16_f32 v32, v32, v33
	s_nop 0
	v_cvt_pk_bf16_f32 v33, v34, v35
	global_store_dwordx2 v[56:57], v[32:33], off offset:1024
	global_load_dwordx4 v[32:35], v[54:55], off offset:3072
	s_nop 0
	global_load_dwordx4 v[36:39], v[52:53], off offset:3072
	s_waitcnt vmcnt(1)
	v_pk_add_f32 v[32:33], v[32:33], 1.0 op_sel_hi:[1,0]
	v_pk_add_f32 v[34:35], v[34:35], 1.0 op_sel_hi:[1,0]
	s_waitcnt vmcnt(0)
	v_pk_fma_f32 v[16:17], v[16:17], v[32:33], v[36:37]
	v_pk_fma_f32 v[18:19], v[18:19], v[34:35], v[38:39]
	v_cvt_pk_bf16_f32 v16, v16, v17
	s_nop 0
	v_cvt_pk_bf16_f32 v17, v18, v19
	global_store_dwordx2 v[56:57], v[16:17], off offset:1536
	s_cbranch_scc1 .LBB0_1146
